# priority raise for the younger of the two co-resident waves now selected by the hardware wave slot (HW_ID.WAVE_ID bit 0) instead of workgroup id bit 8
# speedup vs baseline: 1.0034x; 1.0034x over previous
.LBB0_7:
	s_mov_b32 s38, s42
	s_mov_b32 s0, 0x1bff
	s_bitcmp1_b32 s0, s42
	s_cbranch_scc0 .Lgemm_np
	s_getreg_b32 s0, hwreg(HW_REG_HW_ID, 0, 4)
	s_bitcmp1_b32 s0, 0
	s_cbranch_scc0 .Lgemm_np
	s_setprio 1

.Lattn_ld:
	global_load_dwordx4 v[164:167], v[190:191], off
	global_load_dwordx4 v[148:151], v[190:191], off offset:64
	global_load_dwordx4 v[152:155], v[190:191], off offset:128
	global_load_dwordx4 v[172:175], v[190:191], off offset:192
	global_load_dwordx4 v[156:159], v[242:243], off
	global_load_dwordx4 v[160:163], v[242:243], off offset:64
	v_add_co_u32_e32 v190, vcc, s79, v252
	s_nop 1
	v_addc_co_u32_e32 v191, vcc, 0, v253, vcc
	global_load_dwordx4 v[144:147], v[252:253], off
	global_load_dwordx4 v[168:171], v[190:191], off
	v_add_co_u32_e32 v190, vcc, 0x100000, v252
	s_nop 1
	v_addc_co_u32_e32 v191, vcc, 0, v253, vcc
	v_add_co_u32_e32 v242, vcc, 0x180000, v252
	s_nop 1
	v_addc_co_u32_e32 v243, vcc, 0, v253, vcc
	global_load_dwordx4 v[176:179], v[190:191], off
	global_load_dwordx4 v[180:183], v[242:243], off
	s_cmp_le_i32 s15, s17
	s_cbranch_scc0 .LBB0_57
	s_setprio 1
	s_waitcnt lgkmcnt(7)
	v_mfma_f32_32x32x16_bf16 v[80:95], v[244:247], v[96:99], 0
	ds_read_b128 v[244:247], v220 offset:256
	s_waitcnt lgkmcnt(7)
	v_mfma_f32_32x32x16_bf16 v[80:95], v[248:251], v[100:103], v[80:95]
	ds_read_b128 v[248:251], v220 offset:288
	s_waitcnt lgkmcnt(7)
	v_mfma_f32_32x32x16_bf16 v[80:95], v[222:225], v[104:107], v[80:95]
	ds_read_b128 v[222:225], v220 offset:320
	s_waitcnt lgkmcnt(7)
	v_mfma_f32_32x32x16_bf16 v[80:95], v[230:233], v[108:111], v[80:95]
	ds_read_b128 v[230:233], v220 offset:352
	s_waitcnt lgkmcnt(7)
	v_mfma_f32_32x32x16_bf16 v[80:95], v[64:67], v[112:115], v[80:95]
	s_waitcnt lgkmcnt(6)
	v_mfma_f32_32x32x16_bf16 v[80:95], v[68:71], v[116:119], v[80:95]
	s_waitcnt lgkmcnt(5)
	v_mfma_f32_32x32x16_bf16 v[80:95], v[72:75], v[120:123], v[80:95]
	s_waitcnt lgkmcnt(4)
	v_mfma_f32_32x32x16_bf16 v[80:95], v[76:79], v[124:127], v[80:95]
	s_waitcnt lgkmcnt(3)
	v_mfma_f32_32x32x16_bf16 v[80:95], v[244:247], v[128:131], v[80:95]
	ds_read_b128 v[244:247], v220 offset:12800
	s_waitcnt lgkmcnt(3)
	v_mfma_f32_32x32x16_bf16 v[80:95], v[248:251], v[132:135], v[80:95]
	ds_read_b128 v[248:251], v220 offset:12832
	s_waitcnt lgkmcnt(3)
	v_mfma_f32_32x32x16_bf16 v[80:95], v[222:225], v[136:139], v[80:95]
	ds_read_b128 v[222:225], v220 offset:12864
	s_waitcnt lgkmcnt(3)
	v_mfma_f32_32x32x16_bf16 v[80:95], v[230:233], v[140:143], v[80:95]
	ds_read_b128 v[230:233], v220 offset:12896
	s_waitcnt lgkmcnt(3)
	v_mfma_f32_32x32x16_bf16 v[64:79], v[244:247], v[96:99], 0
	ds_read_b128 v[244:247], v220 offset:12928
	s_waitcnt lgkmcnt(3)
	v_mfma_f32_32x32x16_bf16 v[64:79], v[248:251], v[100:103], v[64:79]
	ds_read_b128 v[248:251], v220 offset:12960
	s_waitcnt lgkmcnt(3)
	v_mfma_f32_32x32x16_bf16 v[64:79], v[222:225], v[104:107], v[64:79]
	ds_read_b128 v[222:225], v220 offset:12992
	s_waitcnt lgkmcnt(3)
	v_mfma_f32_32x32x16_bf16 v[64:79], v[230:233], v[108:111], v[64:79]
	ds_read_b128 v[230:233], v220 offset:13024
	s_waitcnt lgkmcnt(3)
	v_mfma_f32_32x32x16_bf16 v[64:79], v[244:247], v[112:115], v[64:79]
	ds_read_b128 v[244:247], v220 offset:13056
	s_waitcnt lgkmcnt(3)
	v_mfma_f32_32x32x16_bf16 v[64:79], v[248:251], v[116:119], v[64:79]
	ds_read_b128 v[248:251], v220 offset:13088
	s_waitcnt lgkmcnt(3)
	v_mfma_f32_32x32x16_bf16 v[64:79], v[222:225], v[120:123], v[64:79]
	ds_read_b128 v[222:225], v220 offset:13120
	s_waitcnt lgkmcnt(3)
	v_mfma_f32_32x32x16_bf16 v[64:79], v[230:233], v[124:127], v[64:79]
	ds_read_b128 v[230:233], v220 offset:13152
	s_waitcnt lgkmcnt(3)
	v_mfma_f32_32x32x16_bf16 v[64:79], v[244:247], v[128:131], v[64:79]
	s_waitcnt lgkmcnt(2)
	v_mfma_f32_32x32x16_bf16 v[64:79], v[248:251], v[132:135], v[64:79]
	s_waitcnt lgkmcnt(1)
	v_mfma_f32_32x32x16_bf16 v[64:79], v[222:225], v[136:139], v[64:79]
	s_waitcnt lgkmcnt(0)
	v_mfma_f32_32x32x16_bf16 v[64:79], v[230:233], v[140:143], v[64:79]
	s_getreg_b32 s4, hwreg(HW_REG_HW_ID, 0, 4)
	s_bitcmp1_b32 s4, 0
	s_cbranch_scc1 .Lprio_keep0
	s_setprio 0

.Lattn_noresc:
	v_sub_f32_e32 v80, v80, v241
	v_sub_f32_e32 v81, v81, v241
	v_sub_f32_e32 v82, v82, v241
	v_sub_f32_e32 v83, v83, v241
	v_sub_f32_e32 v84, v84, v241
	v_sub_f32_e32 v85, v85, v241
	v_sub_f32_e32 v86, v86, v241
	v_sub_f32_e32 v87, v87, v241
	v_sub_f32_e32 v88, v88, v241
	v_sub_f32_e32 v89, v89, v241
	v_sub_f32_e32 v90, v90, v241
	v_sub_f32_e32 v91, v91, v241
	v_sub_f32_e32 v92, v92, v241
	v_sub_f32_e32 v93, v93, v241
	v_sub_f32_e32 v94, v94, v241
	v_sub_f32_e32 v95, v95, v241
	v_sub_f32_e32 v64, v64, v241
	v_sub_f32_e32 v65, v65, v241
	v_sub_f32_e32 v66, v66, v241
	v_sub_f32_e32 v67, v67, v241
	v_sub_f32_e32 v68, v68, v241
	v_sub_f32_e32 v69, v69, v241
	v_sub_f32_e32 v70, v70, v241
	v_sub_f32_e32 v71, v71, v241
	v_sub_f32_e32 v72, v72, v241
	v_sub_f32_e32 v73, v73, v241
	v_sub_f32_e32 v74, v74, v241
	v_sub_f32_e32 v75, v75, v241
	v_sub_f32_e32 v76, v76, v241
	v_sub_f32_e32 v77, v77, v241
	v_sub_f32_e32 v78, v78, v241
	v_sub_f32_e32 v79, v79, v241
	v_exp_f32_e32 v80, v80
	v_exp_f32_e32 v81, v81
	v_exp_f32_e32 v82, v82
	v_add_f32_e32 v221, v80, v81
	v_exp_f32_e32 v83, v83
	v_add_f32_e32 v221, v221, v82
	v_exp_f32_e32 v84, v84
	v_add_f32_e32 v221, v221, v83
	v_exp_f32_e32 v85, v85
	v_add_f32_e32 v221, v221, v84
	v_exp_f32_e32 v86, v86
	v_add_f32_e32 v221, v221, v85
	v_exp_f32_e32 v87, v87
	v_add_f32_e32 v221, v221, v86
	v_exp_f32_e32 v88, v88
	v_add_f32_e32 v221, v221, v87
	v_exp_f32_e32 v89, v89
	v_add_f32_e32 v221, v221, v88
	v_exp_f32_e32 v90, v90
	v_add_f32_e32 v221, v221, v89
	v_exp_f32_e32 v91, v91
	v_add_f32_e32 v221, v221, v90
	v_exp_f32_e32 v92, v92
	v_add_f32_e32 v221, v221, v91
	v_exp_f32_e32 v93, v93
	v_add_f32_e32 v221, v221, v92
	v_exp_f32_e32 v94, v94
	v_add_f32_e32 v221, v221, v93
	v_exp_f32_e32 v95, v95
	v_add_f32_e32 v221, v221, v94
	v_exp_f32_e32 v64, v64
	v_add_f32_e32 v221, v221, v95
	v_exp_f32_e32 v65, v65
	v_add_f32_e32 v221, v221, v64
	v_exp_f32_e32 v66, v66
	v_add_f32_e32 v221, v221, v65
	v_exp_f32_e32 v67, v67
	v_add_f32_e32 v221, v221, v66
	v_exp_f32_e32 v68, v68
	v_add_f32_e32 v221, v221, v67
	v_exp_f32_e32 v69, v69
	v_add_f32_e32 v221, v221, v68
	v_exp_f32_e32 v70, v70
	v_add_f32_e32 v221, v221, v69
	v_exp_f32_e32 v71, v71
	v_add_f32_e32 v221, v221, v70
	v_exp_f32_e32 v72, v72
	v_add_f32_e32 v221, v221, v71
	v_exp_f32_e32 v73, v73
	v_add_f32_e32 v221, v221, v72
	v_exp_f32_e32 v74, v74
	v_add_f32_e32 v221, v221, v73
	v_exp_f32_e32 v75, v75
	v_add_f32_e32 v221, v221, v74
	v_exp_f32_e32 v76, v76
	v_add_f32_e32 v221, v221, v75
	v_exp_f32_e32 v77, v77
	v_add_f32_e32 v221, v221, v76
	v_exp_f32_e32 v78, v78
	v_add_f32_e32 v221, v221, v77
	v_exp_f32_e32 v79, v79
	v_add_f32_e32 v221, v221, v78
	s_nop 0
	v_add_f32_e32 v221, v221, v79
	v_fmac_f32_e32 v221, v215, v220
	v_cvt_pk_bf16_f32 v80, v80, v81
	v_cvt_pk_bf16_f32 v81, v82, v83
	v_cvt_pk_bf16_f32 v82, v84, v85
	v_cvt_pk_bf16_f32 v83, v86, v87
	v_cvt_pk_bf16_f32 v88, v88, v89
	v_cvt_pk_bf16_f32 v89, v90, v91
	v_cvt_pk_bf16_f32 v90, v92, v93
	v_cvt_pk_bf16_f32 v91, v94, v95
	v_cvt_pk_bf16_f32 v64, v64, v65
	v_cvt_pk_bf16_f32 v65, v66, v67
	v_cvt_pk_bf16_f32 v66, v68, v69
	v_cvt_pk_bf16_f32 v67, v70, v71
	v_cvt_pk_bf16_f32 v72, v72, v73
	v_cvt_pk_bf16_f32 v73, v74, v75
	v_cvt_pk_bf16_f32 v74, v76, v77
	v_cvt_pk_bf16_f32 v75, v78, v79
	v_mov_b32_e32 v215, v221
	v_mov_b32_e32 v240, v241
	ds_read_b128 v[84:87], v239 offset:25632
	ds_read_b128 v[92:95], v239 offset:30240
	ds_read_b128 v[68:71], v239 offset:34848
	ds_read_b128 v[76:79], v239 offset:39456
	s_setprio 1
	s_waitcnt lgkmcnt(7)
	v_mfma_f32_32x32x16_bf16 v[48:63], v[244:247], v[80:83], v[48:63]
	ds_read_b128 v[244:247], v239 offset:25664
	s_waitcnt lgkmcnt(7)
	v_mfma_f32_32x32x16_bf16 v[32:47], v[248:251], v[80:83], v[32:47]
	ds_read_b128 v[248:251], v239 offset:30272
	s_waitcnt lgkmcnt(7)
	v_mfma_f32_32x32x16_bf16 v[16:31], v[222:225], v[80:83], v[16:31]
	ds_read_b128 v[222:225], v239 offset:34880
	s_waitcnt lgkmcnt(7)
	v_mfma_f32_32x32x16_bf16 v[0:15], v[230:233], v[80:83], v[0:15]
	ds_read_b128 v[230:233], v239 offset:39488
	s_waitcnt lgkmcnt(7)
	v_mfma_f32_32x32x16_bf16 v[48:63], v[84:87], v[88:91], v[48:63]
	ds_read_b128 v[84:87], v239 offset:25696
	s_waitcnt lgkmcnt(7)
	v_mfma_f32_32x32x16_bf16 v[32:47], v[92:95], v[88:91], v[32:47]
	ds_read_b128 v[92:95], v239 offset:30304
	s_waitcnt lgkmcnt(7)
	v_mfma_f32_32x32x16_bf16 v[16:31], v[68:71], v[88:91], v[16:31]
	ds_read_b128 v[68:71], v239 offset:34912
	s_waitcnt lgkmcnt(7)
	v_mfma_f32_32x32x16_bf16 v[0:15], v[76:79], v[88:91], v[0:15]
	ds_read_b128 v[76:79], v239 offset:39520
	s_waitcnt lgkmcnt(7)
	v_mfma_f32_32x32x16_bf16 v[48:63], v[244:247], v[64:67], v[48:63]
	s_waitcnt lgkmcnt(6)
	v_mfma_f32_32x32x16_bf16 v[32:47], v[248:251], v[64:67], v[32:47]
	s_waitcnt lgkmcnt(5)
	v_mfma_f32_32x32x16_bf16 v[16:31], v[222:225], v[64:67], v[16:31]
	s_waitcnt lgkmcnt(4)
	v_mfma_f32_32x32x16_bf16 v[0:15], v[230:233], v[64:67], v[0:15]
	s_waitcnt lgkmcnt(3)
	v_mfma_f32_32x32x16_bf16 v[48:63], v[84:87], v[72:75], v[48:63]
	s_waitcnt lgkmcnt(2)
	v_mfma_f32_32x32x16_bf16 v[32:47], v[92:95], v[72:75], v[32:47]
	s_waitcnt lgkmcnt(1)
	v_mfma_f32_32x32x16_bf16 v[16:31], v[68:71], v[72:75], v[16:31]
	s_waitcnt lgkmcnt(0)
	v_mfma_f32_32x32x16_bf16 v[0:15], v[76:79], v[72:75], v[0:15]
	s_getreg_b32 s4, hwreg(HW_REG_HW_ID, 0, 4)
	s_bitcmp1_b32 s4, 0
	s_cbranch_scc1 .Lprio_keep1
	s_setprio 0
